# v3_splitpk
# speedup vs baseline: 1.0208x; 1.0208x over previous
; #define ATT_QK(S0_, S1_, kf_) do { \
;     _Pragma("unroll") for (int i_ = 0; i_ < 16; ++i_) { S0_[i_] = 0.f; S1_[i_] = 0.f; } \
;     _Pragma("unroll") for (int kk_ = 0; kk_ < 4; ++kk_) { \
;       S0_ = __builtin_amdgcn_mfma_f32_32x32x16_bf16(kf_[kk_], qf[0][kk_], S0_, 0, 0, 0); \
;       S1_ = __builtin_amdgcn_mfma_f32_32x32x16_bf16(kf_[kk_], qf[1][kk_], S1_, 0, 0, 0); } } while (0)
; #define ATT_PV(vf_, P0_, P1_) do { \
;     _Pragma("unroll") for (int c_ = 0; c_ < 2; ++c_) \
;     _Pragma("unroll") for (int db_ = 0; db_ < 2; ++db_) { \
;       O[db_][0] = __builtin_amdgcn_mfma_f32_32x32x16_bf16(vf_[db_ * 2 + c_], P0_[c_], O[db_][0], 0, 0, 0); \
;       O[db_][1] = __builtin_amdgcn_mfma_f32_32x32x16_bf16(vf_[db_ * 2 + c_], P1_[c_], O[db_][1], 0, 0, 0); } } while (0)
; __device__ __forceinline__ void exp_pack(f32x16& s, float& l, bf16x8& p0, bf16x8& p1) {
; #pragma unroll
;   for (int i = 0; i < 16; ++i) s[i] = __builtin_amdgcn_exp2f(s[i]);
;   const float a0 = (s[0] + s[1]) + (s[2] + s[3]), a1 = (s[4] + s[5]) + (s[6] + s[7]);
;   const float a2 = (s[8] + s[9]) + (s[10] + s[11]), a3 = (s[12] + s[13]) + (s[14] + s[15]);
;   l += (a0 + a1) + (a2 + a3);
;   p0 = pack8(s, 0); p1 = pack8(s, 8);
; }
; __device__ __forceinline__ void attn_item_fast(const u16* __restrict__ Qg, const u16* __restrict__ Kg, const u16* __restrict__ Vtg,
;                                                u16* __restrict__ Og, const int L, char* smem, const int tid) {
;     ...
;   for (int t = 0; t < NT; ++t) {
;     const int cur = (t & 1) * 8192;
;     const char* Kb = Ks + cur; const char* Vb = Vs + cur;
;     if (t + 1 < NT) {
;       const char* kb_ = (const char*)Kg + (size_t)(t + 1) * (64 * 256 * 2);
;       const char* vb_ = (const char*)Vtg + (size_t)(t + 1) * 128;
;       glds16(koff, kb_, ldsK + (unsigned)(cur ^ 8192)); glds16(voff, vb_, ldsV + (unsigned)(cur ^ 8192));
;     }
;     ld_kf<0>(kf, Kb, r32, hi, sw);
;     ATT_PV(vf, P0, P1);
;     ld_vf<0>(vf, Vb, r32, hi, sw);
;     ATT_QK(S0, S1, kf);
;     ld_kf<1>(kf, Kb, r32, hi, sw);
;     WBAR();
;     exp_pack(S0, l0, P0[0], P0[1]); exp_pack(S1, l1, P1[0], P1[1]);
;     WBAR();
;     ATT_PV(vf, P0, P1);
;     ld_vf<1>(vf, Vb, r32, hi, sw);
;     ATT_QK(S0, S1, kf);
;     asm volatile("s_waitcnt vmcnt(0) lgkmcnt(0)" ::: "memory");
;     WBAR();
;     exp_pack(S0, l0, P0[0], P0[1]); exp_pack(S1, l1, P1[0], P1[1]);
;     WBAR();
.LBB0_93:
	s_and_b32 s3, s53, 0x2000
	s_xor_b32 s13, s3, 0x2000
	s_add_i32 s15, s13, s49
	s_add_i32 s13, s13, s48
	s_mov_b32 s52, m0
	s_mov_b32 m0, s13
	s_nop 0
	global_load_lds_dwordx4 v179, s[34:35]
	s_mov_b32 m0, s52
	v_add_u32_e32 v82, s3, v181
	s_mov_b32 s13, m0
	s_mov_b32 m0, s15
	s_nop 0
	global_load_lds_dwordx4 v180, s[38:39]
	s_mov_b32 m0, s13
	v_add_u32_e32 v188, v82, v182
	ds_read_b128 v[146:149], v188
	s_waitcnt lgkmcnt(4)
	v_mfma_f32_32x32x16_bf16 v[50:65], v[142:145], v[74:77], v[50:65]
	v_add_u32_e32 v189, v82, v183
	ds_read_b128 v[150:153], v189
	v_add_u32_e32 v186, v82, v184
	v_add_u32_e32 v187, v82, v185
	ds_read_b128 v[154:157], v186
	ds_read_b128 v[158:161], v187
	v_mfma_f32_32x32x16_bf16 v[18:33], v[142:145], v[78:81], v[18:33]
	s_waitcnt lgkmcnt(6)
	v_mfma_f32_32x32x16_bf16 v[34:49], v[138:141], v[74:77], v[34:49]
	v_mfma_f32_32x32x16_bf16 v[2:17], v[138:141], v[78:81], v[2:17]
	s_waitcnt lgkmcnt(5)
	v_mfma_f32_32x32x16_bf16 v[50:65], v[134:137], v[70:73], v[50:65]
	v_mfma_f32_32x32x16_bf16 v[18:33], v[134:137], v[66:69], v[18:33]
	s_waitcnt lgkmcnt(4)
	v_mfma_f32_32x32x16_bf16 v[34:49], v[130:133], v[70:73], v[34:49]
	v_mfma_f32_32x32x16_bf16 v[2:17], v[130:133], v[66:69], v[2:17]
	ds_read_b128 v[142:145], v188 offset:16384
	ds_read_b128 v[134:137], v189 offset:16384
	ds_read_b128 v[138:141], v188 offset:20480
	ds_read_b128 v[130:133], v189 offset:20480
	s_waitcnt lgkmcnt(7)
	v_mfma_f32_32x32x16_bf16 v[66:81], v[146:149], v[126:129], 0
	v_mfma_f32_32x32x16_bf16 v[82:97], v[146:149], v[118:121], 0
	s_waitcnt lgkmcnt(6)
	v_mfma_f32_32x32x16_bf16 v[66:81], v[150:153], v[122:125], v[66:81]
	v_mfma_f32_32x32x16_bf16 v[82:97], v[150:153], v[114:117], v[82:97]
	s_waitcnt lgkmcnt(5)
	v_mfma_f32_32x32x16_bf16 v[66:81], v[154:157], v[110:113], v[66:81]
	v_mfma_f32_32x32x16_bf16 v[82:97], v[154:157], v[106:109], v[82:97]
	s_waitcnt lgkmcnt(4)
	v_mfma_f32_32x32x16_bf16 v[66:81], v[158:161], v[98:101], v[66:81]
	v_mfma_f32_32x32x16_bf16 v[82:97], v[158:161], v[102:105], v[82:97]
	ds_read_b128 v[146:149], v188 offset:4096
	ds_read_b128 v[150:153], v189 offset:4096
	ds_read_b128 v[154:157], v186 offset:4096
	ds_read_b128 v[158:161], v187 offset:4096
	s_barrier
	s_nop 6
	v_exp_f32_e32 v82, v82
	v_exp_f32_e32 v188, v83
	v_exp_f32_e32 v84, v84
	v_exp_f32_e32 v206, v85
	v_exp_f32_e32 v83, v66
	v_exp_f32_e32 v189, v67
	v_exp_f32_e32 v85, v68
	v_exp_f32_e32 v207, v69
	v_exp_f32_e32 v86, v86
	v_exp_f32_e32 v208, v87
	v_exp_f32_e32 v88, v88
	v_exp_f32_e32 v210, v89
	v_exp_f32_e32 v87, v70
	v_exp_f32_e32 v209, v71
	v_exp_f32_e32 v89, v72
	v_exp_f32_e32 v211, v73
	v_exp_f32_e32 v90, v90
	v_exp_f32_e32 v212, v91
	v_exp_f32_e32 v92, v92
	v_exp_f32_e32 v214, v93
	v_exp_f32_e32 v91, v74
	v_exp_f32_e32 v213, v75
	v_exp_f32_e32 v93, v76
	v_exp_f32_e32 v215, v77
	v_exp_f32_e32 v94, v94
	v_exp_f32_e32 v216, v95
	v_exp_f32_e32 v96, v96
	v_exp_f32_e32 v218, v97
	v_exp_f32_e32 v95, v78
	v_exp_f32_e32 v217, v79
	v_exp_f32_e32 v97, v80
	v_exp_f32_e32 v219, v81
	v_add_f32_e32 v74, v82, v188
	v_add_f32_e32 v75, v83, v189
	v_add_f32_e32 v76, v84, v206
	v_add_f32_e32 v77, v85, v207
	v_add_f32_e32 v78, v88, v210
	v_add_f32_e32 v79, v89, v211
	v_add_f32_e32 v74, v74, v76
	v_add_f32_e32 v75, v75, v77
	v_add_f32_e32 v76, v86, v208
	v_add_f32_e32 v77, v87, v209
	v_add_f32_e32 v80, v92, v214
	v_add_f32_e32 v81, v93, v215
	v_add_f32_e32 v76, v76, v78
	v_add_f32_e32 v77, v77, v79
	v_add_f32_e32 v78, v90, v212
	v_add_f32_e32 v79, v91, v213
	v_add_f32_e32 v220, v96, v218
	v_add_f32_e32 v221, v97, v219
	v_add_f32_e32 v78, v78, v80
	v_add_f32_e32 v79, v79, v81
	v_add_f32_e32 v80, v94, v216
	v_add_f32_e32 v81, v95, v217
	v_add_f32_e32 v74, v74, v76
	v_add_f32_e32 v75, v75, v77
	v_add_f32_e32 v80, v80, v220
	v_add_f32_e32 v81, v81, v221
	v_cvt_pk_bf16_f32 v66, v82, v188
	v_cvt_pk_bf16_f32 v67, v84, v206
	v_cvt_pk_bf16_f32 v68, v86, v208
	v_cvt_pk_bf16_f32 v69, v88, v210
	v_cvt_pk_bf16_f32 v70, v90, v212
	s_nop 0
	v_add_f32_e32 v76, v78, v80
	v_add_f32_e32 v77, v79, v81
	v_cvt_pk_bf16_f32 v71, v92, v214
	v_cvt_pk_bf16_f32 v72, v94, v216
	v_cvt_pk_bf16_f32 v73, v96, v218
	v_cvt_pk_bf16_f32 v78, v91, v213
	v_cvt_pk_bf16_f32 v79, v93, v215
	s_nop 0
	v_add_f32_e32 v220, v74, v76
	v_add_f32_e32 v221, v75, v77
	v_cvt_pk_bf16_f32 v74, v83, v189
	v_cvt_pk_bf16_f32 v75, v85, v207
	v_cvt_pk_bf16_f32 v76, v87, v209
	v_cvt_pk_bf16_f32 v77, v89, v211
	v_cvt_pk_bf16_f32 v80, v95, v217
	v_cvt_pk_bf16_f32 v81, v97, v219
	s_barrier
	s_waitcnt lgkmcnt(7)
	v_mfma_f32_32x32x16_bf16 v[50:65], v[142:145], v[66:69], v[50:65]
	v_mfma_f32_32x32x16_bf16 v[18:33], v[142:145], v[74:77], v[18:33]
	s_waitcnt lgkmcnt(5)
	v_mfma_f32_32x32x16_bf16 v[34:49], v[138:141], v[66:69], v[34:49]
	v_mfma_f32_32x32x16_bf16 v[2:17], v[138:141], v[74:77], v[2:17]
	v_mfma_f32_32x32x16_bf16 v[50:65], v[134:137], v[70:73], v[50:65]
	v_mfma_f32_32x32x16_bf16 v[18:33], v[134:137], v[78:81], v[18:33]
	s_waitcnt lgkmcnt(4)
	v_mfma_f32_32x32x16_bf16 v[34:49], v[130:133], v[70:73], v[34:49]
	v_mfma_f32_32x32x16_bf16 v[2:17], v[130:133], v[78:81], v[2:17]
	ds_read_b128 v[142:145], v186 offset:16384
	ds_read_b128 v[138:141], v186 offset:20480
	ds_read_b128 v[134:137], v187 offset:16384
	ds_read_b128 v[130:133], v187 offset:20480
	s_waitcnt vmcnt(0) lgkmcnt(0)
	s_waitcnt lgkmcnt(7)
	v_mfma_f32_32x32x16_bf16 v[66:81], v[146:149], v[126:129], 0
	v_mfma_f32_32x32x16_bf16 v[82:97], v[146:149], v[118:121], 0
	v_add_f32_e64 v146, v172, v220
	v_add_f32_e64 v147, v173, v221
	s_waitcnt lgkmcnt(6)
	v_mfma_f32_32x32x16_bf16 v[66:81], v[150:153], v[122:125], v[66:81]
	v_mfma_f32_32x32x16_bf16 v[82:97], v[150:153], v[114:117], v[82:97]
	s_waitcnt lgkmcnt(5)
	v_mfma_f32_32x32x16_bf16 v[66:81], v[154:157], v[110:113], v[66:81]
	v_mfma_f32_32x32x16_bf16 v[82:97], v[154:157], v[106:109], v[82:97]
	s_waitcnt lgkmcnt(4)
	v_mfma_f32_32x32x16_bf16 v[66:81], v[158:161], v[98:101], v[66:81]
	v_mfma_f32_32x32x16_bf16 v[82:97], v[158:161], v[102:105], v[82:97]
	s_barrier
; #define ATT_QK(S0_, S1_, kf_) do { \
;     _Pragma("unroll") for (int i_ = 0; i_ < 16; ++i_) { S0_[i_] = 0.f; S1_[i_] = 0.f; } \
;     _Pragma("unroll") for (int kk_ = 0; kk_ < 4; ++kk_) { \
;       S0_ = __builtin_amdgcn_mfma_f32_32x32x16_bf16(kf_[kk_], qf[0][kk_], S0_, 0, 0, 0); \
;       S1_ = __builtin_amdgcn_mfma_f32_32x32x16_bf16(kf_[kk_], qf[1][kk_], S1_, 0, 0, 0); } } while (0)
; #define ATT_PV(vf_, P0_, P1_) do { \
;     _Pragma("unroll") for (int c_ = 0; c_ < 2; ++c_) \
;     _Pragma("unroll") for (int db_ = 0; db_ < 2; ++db_) { \
;       O[db_][0] = __builtin_amdgcn_mfma_f32_32x32x16_bf16(vf_[db_ * 2 + c_], P0_[c_], O[db_][0], 0, 0, 0); \
;       O[db_][1] = __builtin_amdgcn_mfma_f32_32x32x16_bf16(vf_[db_ * 2 + c_], P1_[c_], O[db_][1], 0, 0, 0); } } while (0)
; #define WBAR() do { __builtin_amdgcn_sched_barrier(0); __builtin_amdgcn_s_barrier(); __builtin_amdgcn_sched_barrier(0); } while (0)
; __device__ __forceinline__ void exp_pack(f32x16& s, float& l, bf16x8& p0, bf16x8& p1) {
; #pragma unroll
;   for (int i = 0; i < 16; ++i) s[i] = __builtin_amdgcn_exp2f(s[i]);
;   const float a0 = (s[0] + s[1]) + (s[2] + s[3]), a1 = (s[4] + s[5]) + (s[6] + s[7]);
;   const float a2 = (s[8] + s[9]) + (s[10] + s[11]), a3 = (s[12] + s[13]) + (s[14] + s[15]);
;   l += (a0 + a1) + (a2 + a3);
;   p0 = pack8(s, 0); p1 = pack8(s, 8);
; }
; __device__ __forceinline__ void attn_item_fast(const u16* __restrict__ Qg, const u16* __restrict__ Kg, const u16* __restrict__ Vtg,
;                                                u16* __restrict__ Og, const int L, char* smem, const int tid) {
;     ...
;     exp_pack(S0, l0, P0[0], P0[1]); exp_pack(S1, l1, P1[0], P1[1]);
;     WBAR();
;     ATT_PV(vf, P0, P1);
;     ld_vf<1>(vf, Vb, r32, hi, sw);
;     ATT_QK(S0, S1, kf);
;     asm volatile("s_waitcnt vmcnt(0) lgkmcnt(0)" ::: "memory");
;     WBAR();
;     exp_pack(S0, l0, P0[0], P0[1]); exp_pack(S1, l1, P1[0], P1[1]);
;     WBAR();
	s_nop 10
	v_exp_f32_e32 v82, v82
	v_exp_f32_e32 v148, v83
	v_exp_f32_e32 v84, v84
	v_exp_f32_e32 v150, v85
	v_exp_f32_e32 v83, v66
	v_exp_f32_e32 v149, v67
	v_exp_f32_e32 v85, v68
	v_exp_f32_e32 v151, v69
	v_exp_f32_e32 v86, v86
	v_exp_f32_e32 v152, v87
	v_exp_f32_e32 v88, v88
	v_exp_f32_e32 v154, v89
	v_exp_f32_e32 v87, v70
	v_exp_f32_e32 v153, v71
	v_exp_f32_e32 v89, v72
	v_exp_f32_e32 v155, v73
	v_exp_f32_e32 v90, v90
	v_exp_f32_e32 v156, v91
	v_exp_f32_e32 v92, v92
	v_exp_f32_e32 v158, v93
	v_exp_f32_e32 v91, v74
	v_exp_f32_e32 v157, v75
	v_exp_f32_e32 v93, v76
	v_exp_f32_e32 v159, v77
	v_exp_f32_e32 v94, v94
	v_exp_f32_e32 v160, v95
	v_exp_f32_e32 v96, v96
	v_exp_f32_e32 v186, v97
	v_exp_f32_e32 v95, v78
	v_exp_f32_e32 v161, v79
	v_exp_f32_e32 v97, v80
	v_exp_f32_e32 v187, v81
	v_add_f32_e32 v66, v82, v148
	v_add_f32_e32 v67, v83, v149
	v_add_f32_e32 v68, v84, v150
	v_add_f32_e32 v69, v85, v151
	v_add_f32_e32 v70, v88, v154
	v_add_f32_e32 v71, v89, v155
	v_add_f32_e32 v66, v66, v68
	v_add_f32_e32 v67, v67, v69
	v_add_f32_e32 v68, v86, v152
	v_add_f32_e32 v69, v87, v153
	v_add_f32_e32 v72, v92, v158
	v_add_f32_e32 v73, v93, v159
	v_add_f32_e32 v68, v68, v70
	v_add_f32_e32 v69, v69, v71
	v_add_f32_e32 v70, v90, v156
	v_add_f32_e32 v71, v91, v157
	v_add_f32_e32 v74, v96, v186
	v_add_f32_e32 v75, v97, v187
	v_add_f32_e32 v70, v70, v72
	v_add_f32_e32 v71, v71, v73
	v_add_f32_e32 v72, v94, v160
	v_add_f32_e32 v73, v95, v161
	v_add_f32_e32 v66, v66, v68
	v_add_f32_e32 v67, v67, v69
	v_add_f32_e32 v72, v72, v74
	v_add_f32_e32 v73, v73, v75
	v_cvt_pk_bf16_f32 v74, v82, v148
	v_cvt_pk_bf16_f32 v75, v84, v150
	v_cvt_pk_bf16_f32 v76, v86, v152
	v_cvt_pk_bf16_f32 v77, v88, v154
	v_cvt_pk_bf16_f32 v78, v83, v149
	s_nop 0
	v_add_f32_e32 v68, v70, v72
	v_add_f32_e32 v69, v71, v73
	v_cvt_pk_bf16_f32 v70, v90, v156
	v_cvt_pk_bf16_f32 v71, v92, v158
	v_cvt_pk_bf16_f32 v72, v94, v160
	v_cvt_pk_bf16_f32 v73, v96, v186
	v_cvt_pk_bf16_f32 v79, v85, v151
	s_nop 0
	v_add_f32_e32 v66, v66, v68
	v_add_f32_e32 v67, v67, v69
	v_cvt_pk_bf16_f32 v80, v87, v153
	v_cvt_pk_bf16_f32 v81, v89, v155
	v_cvt_pk_bf16_f32 v68, v95, v161
	v_cvt_pk_bf16_f32 v69, v97, v187
	s_nop 0
	v_add_f32_e32 v172, v146, v66
	v_add_f32_e32 v173, v147, v67
	v_cvt_pk_bf16_f32 v66, v91, v157
	v_cvt_pk_bf16_f32 v67, v93, v159
	s_barrier
	s_addk_i32 s53, 0x2000
	s_add_u32 s34, s34, 0x8000
	s_addc_u32 s35, s35, 0
	s_add_u32 s38, s38, 0x80
	s_addc_u32 s39, s39, 0
	s_cmp_eq_u32 s53, 0x1fe000
	s_cbranch_scc0 .LBB0_93
	v_add_u32_e32 v205, v181, v182
	ds_read_b128 v[146:149], v205 offset:8192
	s_waitcnt lgkmcnt(4)
	v_mfma_f32_32x32x16_bf16 v[50:65], v[142:145], v[74:77], v[50:65]
	v_add_u32_e32 v222, v181, v183
	ds_read_b128 v[150:153], v222 offset:8192
	v_add_u32_e32 v234, v181, v184
	ds_read_b128 v[154:157], v234 offset:8192
	v_add_u32_e32 v235, v181, v185
	ds_read_b128 v[158:161], v235 offset:8192
	ds_read_b128 v[186:189], v205 offset:24576
	ds_read_b128 v[206:209], v222 offset:24576
	ds_read_b128 v[210:213], v205 offset:28672
	ds_read_b128 v[214:217], v222 offset:28672
	v_mfma_f32_32x32x16_bf16 v[18:33], v[142:145], v[78:81], v[18:33]
	ds_read_b128 v[218:221], v205 offset:12288
	ds_read_b128 v[222:225], v222 offset:12288
	ds_read_b128 v[226:229], v234 offset:12288
	ds_read_b128 v[230:233], v235 offset:12288
	s_waitcnt lgkmcnt(14)
	v_mfma_f32_32x32x16_bf16 v[34:49], v[138:141], v[74:77], v[34:49]
	v_mfma_f32_32x32x16_bf16 v[2:17], v[138:141], v[78:81], v[2:17]
	s_waitcnt lgkmcnt(13)
	v_mfma_f32_32x32x16_bf16 v[50:65], v[134:137], v[70:73], v[50:65]
	v_mfma_f32_32x32x16_bf16 v[18:33], v[134:137], v[66:69], v[18:33]
	s_waitcnt lgkmcnt(12)
	v_mfma_f32_32x32x16_bf16 v[34:49], v[130:133], v[70:73], v[34:49]
	v_mfma_f32_32x32x16_bf16 v[2:17], v[130:133], v[66:69], v[2:17]
	s_waitcnt lgkmcnt(11)
	v_mfma_f32_32x32x16_bf16 v[82:97], v[146:149], v[118:121], 0
	v_mfma_f32_32x32x16_bf16 v[66:81], v[146:149], v[126:129], 0
	s_waitcnt lgkmcnt(10)
	v_mfma_f32_32x32x16_bf16 v[82:97], v[150:153], v[114:117], v[82:97]
	v_mfma_f32_32x32x16_bf16 v[66:81], v[150:153], v[122:125], v[66:81]
	s_waitcnt lgkmcnt(9)
	v_mfma_f32_32x32x16_bf16 v[82:97], v[154:157], v[106:109], v[82:97]
	v_mfma_f32_32x32x16_bf16 v[66:81], v[154:157], v[110:113], v[66:81]
	s_waitcnt lgkmcnt(8)
	v_mfma_f32_32x32x16_bf16 v[82:97], v[158:161], v[102:105], v[82:97]
	v_mfma_f32_32x32x16_bf16 v[66:81], v[158:161], v[98:101], v[66:81]
	s_barrier
; #define ATT_QK(S0_, S1_, kf_) do { \
;     _Pragma("unroll") for (int i_ = 0; i_ < 16; ++i_) { S0_[i_] = 0.f; S1_[i_] = 0.f; } \
;     _Pragma("unroll") for (int kk_ = 0; kk_ < 4; ++kk_) { \
;       S0_ = __builtin_amdgcn_mfma_f32_32x32x16_bf16(kf_[kk_], qf[0][kk_], S0_, 0, 0, 0); \
;       S1_ = __builtin_amdgcn_mfma_f32_32x32x16_bf16(kf_[kk_], qf[1][kk_], S1_, 0, 0, 0); } } while (0)
; #define ATT_PV(vf_, P0_, P1_) do { \
;     _Pragma("unroll") for (int c_ = 0; c_ < 2; ++c_) \
;     _Pragma("unroll") for (int db_ = 0; db_ < 2; ++db_) { \
;       O[db_][0] = __builtin_amdgcn_mfma_f32_32x32x16_bf16(vf_[db_ * 2 + c_], P0_[c_], O[db_][0], 0, 0, 0); \
;       O[db_][1] = __builtin_amdgcn_mfma_f32_32x32x16_bf16(vf_[db_ * 2 + c_], P1_[c_], O[db_][1], 0, 0, 0); } } while (0)
; #define WBAR() do { __builtin_amdgcn_sched_barrier(0); __builtin_amdgcn_s_barrier(); __builtin_amdgcn_sched_barrier(0); } while (0)
; __device__ __forceinline__ void attn_item_fast(const u16* __restrict__ Qg, const u16* __restrict__ Kg, const u16* __restrict__ Vtg,
;                                                u16* __restrict__ Og, const int L, char* smem, const int tid) {
;     ...
;     ld_kf<0>(kf, Kb, r32, hi, sw);
;     ATT_PV(vf, P0, P1);
;     ld_vf<0>(vf, Vb, r32, hi, sw);
;     ATT_QK(S0, S1, kf);
;     ld_kf<1>(kf, Kb, r32, hi, sw);
;     WBAR();
;     exp_pack(S0, l0, P0[0], P0[1]); exp_pack(S1, l1, P1[0], P1[1]);
;     WBAR();
;     ATT_PV(vf, P0, P1);
;     ld_vf<1>(vf, Vb, r32, hi, sw);
;     ATT_QK(S0, S1, kf);
;     asm volatile("s_waitcnt vmcnt(0) lgkmcnt(0)" ::: "memory");
;     WBAR();
;     exp_pack(S0, l0, P0[0], P0[1]); exp_pack(S1, l1, P1[0], P1[1]);
;     WBAR();
;   }
;   if (half == 0) WBAR();
	s_nop 9
	v_exp_f32_e32 v138, v82
	v_exp_f32_e32 v144, v83
	v_exp_f32_e32 v132, v84
	v_exp_f32_e32 v139, v85
	v_exp_f32_e32 v133, v86
	v_exp_f32_e32 v140, v87
	v_exp_f32_e32 v141, v88
	v_exp_f32_e32 v145, v89
	v_exp_f32_e32 v134, v90
	v_exp_f32_e32 v142, v91
	v_exp_f32_e32 v130, v92
	v_exp_f32_e32 v135, v93
	v_exp_f32_e32 v131, v94
	v_exp_f32_e32 v136, v95
	v_exp_f32_e32 v137, v96
	v_exp_f32_e32 v143, v97
	v_exp_f32_e32 v146, v66
	v_exp_f32_e32 v147, v67
	v_exp_f32_e32 v148, v68
	v_exp_f32_e32 v151, v69
	v_exp_f32_e32 v149, v70
	v_exp_f32_e32 v152, v71
	v_exp_f32_e32 v153, v72
	v_exp_f32_e32 v157, v73
	v_exp_f32_e32 v150, v74
	v_exp_f32_e32 v154, v75
	v_exp_f32_e32 v155, v76
	v_exp_f32_e32 v158, v77
	v_exp_f32_e32 v156, v78
	v_exp_f32_e32 v159, v79
	v_exp_f32_e32 v160, v80
	v_exp_f32_e32 v161, v81
	v_cvt_pk_bf16_f32 v82, v138, v144
	v_cvt_pk_bf16_f32 v83, v132, v139
	v_cvt_pk_bf16_f32 v84, v133, v140
	v_cvt_pk_bf16_f32 v85, v141, v145
	v_cvt_pk_bf16_f32 v86, v134, v142
	v_cvt_pk_bf16_f32 v87, v130, v135
	v_cvt_pk_bf16_f32 v88, v131, v136
	v_cvt_pk_bf16_f32 v89, v137, v143
	v_cvt_pk_bf16_f32 v66, v146, v147
	v_cvt_pk_bf16_f32 v67, v148, v151
	v_cvt_pk_bf16_f32 v68, v149, v152
	v_cvt_pk_bf16_f32 v69, v153, v157
	v_cvt_pk_bf16_f32 v70, v150, v154
	v_cvt_pk_bf16_f32 v71, v155, v158
	v_cvt_pk_bf16_f32 v72, v156, v159
	v_cvt_pk_bf16_f32 v73, v160, v161
	s_barrier
	s_waitcnt lgkmcnt(7)
	v_mfma_f32_32x32x16_bf16 v[50:65], v[186:189], v[82:85], v[50:65]
	v_mfma_f32_32x32x16_bf16 v[18:33], v[186:189], v[66:69], v[18:33]
	s_waitcnt lgkmcnt(5)
	v_mfma_f32_32x32x16_bf16 v[34:49], v[210:213], v[82:85], v[34:49]
	v_mfma_f32_32x32x16_bf16 v[2:17], v[210:213], v[66:69], v[2:17]
	v_mfma_f32_32x32x16_bf16 v[50:65], v[206:209], v[86:89], v[50:65]
	v_mfma_f32_32x32x16_bf16 v[18:33], v[206:209], v[70:73], v[18:33]
	s_waitcnt lgkmcnt(4)
	v_mfma_f32_32x32x16_bf16 v[34:49], v[214:217], v[86:89], v[34:49]
	v_mfma_f32_32x32x16_bf16 v[2:17], v[214:217], v[70:73], v[2:17]
	s_waitcnt lgkmcnt(3)
	v_mfma_f32_32x32x16_bf16 v[82:97], v[218:221], v[118:121], 0
	v_mfma_f32_32x32x16_bf16 v[66:81], v[218:221], v[126:129], 0
	s_waitcnt lgkmcnt(2)
	v_mfma_f32_32x32x16_bf16 v[82:97], v[222:225], v[114:117], v[82:97]
	v_mfma_f32_32x32x16_bf16 v[66:81], v[222:225], v[122:125], v[66:81]
	s_waitcnt lgkmcnt(1)
	v_mfma_f32_32x32x16_bf16 v[82:97], v[226:229], v[106:109], v[82:97]
	v_mfma_f32_32x32x16_bf16 v[66:81], v[226:229], v[110:113], v[66:81]
	s_waitcnt lgkmcnt(0)
	v_mfma_f32_32x32x16_bf16 v[82:97], v[230:233], v[102:105], v[82:97]
	ds_read_b128 v[114:117], v234 offset:24576
	ds_read_b128 v[110:113], v234 offset:28672
	ds_read_b128 v[106:109], v235 offset:24576
	ds_read_b128 v[102:105], v235 offset:28672
	s_waitcnt vmcnt(0) lgkmcnt(0)
	v_mfma_f32_32x32x16_bf16 v[66:81], v[230:233], v[98:101], v[66:81]
	s_barrier
	s_nop 5
	v_exp_f32_e32 v98, v82
	v_exp_f32_e32 v99, v83
	v_exp_f32_e32 v100, v84
	v_exp_f32_e32 v119, v85
	v_exp_f32_e32 v101, v86
	v_exp_f32_e32 v120, v87
	v_exp_f32_e32 v121, v88
	v_exp_f32_e32 v122, v89
	v_exp_f32_e32 v90, v90
	v_exp_f32_e32 v91, v91
	v_exp_f32_e32 v92, v92
	v_exp_f32_e32 v118, v93
	v_exp_f32_e32 v93, v94
	v_exp_f32_e32 v94, v95
	v_exp_f32_e32 v95, v96
	v_exp_f32_e32 v96, v97
	v_exp_f32_e32 v186, v66
	v_exp_f32_e32 v187, v67
	v_exp_f32_e32 v188, v68
	v_exp_f32_e32 v189, v69
	v_exp_f32_e32 v97, v70
	v_exp_f32_e32 v124, v71
	v_exp_f32_e32 v125, v72
	v_exp_f32_e32 v128, v73
	v_exp_f32_e32 v123, v74
	v_exp_f32_e32 v126, v75
	v_exp_f32_e32 v127, v76
	v_exp_f32_e32 v129, v77
	v_exp_f32_e32 v74, v78
	v_exp_f32_e32 v75, v79
	v_exp_f32_e32 v76, v80
	v_exp_f32_e32 v77, v81
	v_cvt_pk_bf16_f32 v86, v98, v99
	v_cvt_pk_bf16_f32 v87, v100, v119
	v_cvt_pk_bf16_f32 v88, v101, v120
	v_cvt_pk_bf16_f32 v89, v121, v122
	v_cvt_pk_bf16_f32 v82, v90, v91
	v_cvt_pk_bf16_f32 v83, v92, v118
	v_cvt_pk_bf16_f32 v84, v93, v94
	v_cvt_pk_bf16_f32 v85, v95, v96
	v_cvt_pk_bf16_f32 v70, v186, v187
	v_cvt_pk_bf16_f32 v71, v188, v189
	v_cvt_pk_bf16_f32 v72, v97, v124
	v_cvt_pk_bf16_f32 v73, v125, v128
	v_cvt_pk_bf16_f32 v66, v123, v126
	v_cvt_pk_bf16_f32 v67, v127, v129
	v_cvt_pk_bf16_f32 v68, v74, v75
	v_cvt_pk_bf16_f32 v69, v76, v77
	s_barrier
	s_cmpk_lt_u32 s14, 0x100
	s_cbranch_scc0 .LBB0_89
	s_barrier
	s_branch .LBB0_89

; #define ATT_QK(S0_, S1_, kf_) do { \
;     _Pragma("unroll") for (int i_ = 0; i_ < 16; ++i_) { S0_[i_] = 0.f; S1_[i_] = 0.f; } \
;     _Pragma("unroll") for (int kk_ = 0; kk_ < 4; ++kk_) { \
;       S0_ = __builtin_amdgcn_mfma_f32_32x32x16_bf16(kf_[kk_], qf[0][kk_], S0_, 0, 0, 0); \
;       S1_ = __builtin_amdgcn_mfma_f32_32x32x16_bf16(kf_[kk_], qf[1][kk_], S1_, 0, 0, 0); } } while (0)
; #define ATT_PV(vf_, P0_, P1_) do { \
;     _Pragma("unroll") for (int c_ = 0; c_ < 2; ++c_) \
;     _Pragma("unroll") for (int db_ = 0; db_ < 2; ++db_) { \
;       O[db_][0] = __builtin_amdgcn_mfma_f32_32x32x16_bf16(vf_[db_ * 2 + c_], P0_[c_], O[db_][0], 0, 0, 0); \
;       O[db_][1] = __builtin_amdgcn_mfma_f32_32x32x16_bf16(vf_[db_ * 2 + c_], P1_[c_], O[db_][1], 0, 0, 0); } } while (0)
; __device__ __forceinline__ void exp_pack(f32x16& s, float& l, bf16x8& p0, bf16x8& p1) {
; #pragma unroll
;   for (int i = 0; i < 16; ++i) s[i] = __builtin_amdgcn_exp2f(s[i]);
;   const float a0 = (s[0] + s[1]) + (s[2] + s[3]), a1 = (s[4] + s[5]) + (s[6] + s[7]);
;   const float a2 = (s[8] + s[9]) + (s[10] + s[11]), a3 = (s[12] + s[13]) + (s[14] + s[15]);
;   l += (a0 + a1) + (a2 + a3);
;   p0 = pack8(s, 0); p1 = pack8(s, 8);
; }
; __device__ __forceinline__ void attn_item_fast(const u16* __restrict__ Qg, const u16* __restrict__ Kg, const u16* __restrict__ Vtg,
;                                                u16* __restrict__ Og, const int L, char* smem, const int tid) {
;     ...
;   for (int t = 0; t < NT; ++t) {
;     const int cur = (t & 1) * 8192;
;     const char* Kb = Ks + cur; const char* Vb = Vs + cur;
;     if (t + 1 < NT) {
;       const char* kb_ = (const char*)Kg + (size_t)(t + 1) * (64 * 256 * 2);
;       const char* vb_ = (const char*)Vtg + (size_t)(t + 1) * 128;
;       glds16(koff, kb_, ldsK + (unsigned)(cur ^ 8192)); glds16(voff, vb_, ldsV + (unsigned)(cur ^ 8192));
;     }
;     ld_kf<0>(kf, Kb, r32, hi, sw);
;     ATT_PV(vf, P0, P1);
;     ld_vf<0>(vf, Vb, r32, hi, sw);
;     ATT_QK(S0, S1, kf);
;     ld_kf<1>(kf, Kb, r32, hi, sw);
;     WBAR();
;     exp_pack(S0, l0, P0[0], P0[1]); exp_pack(S1, l1, P1[0], P1[1]);
;     WBAR();
;     ATT_PV(vf, P0, P1);
;     ld_vf<1>(vf, Vb, r32, hi, sw);
;     ATT_QK(S0, S1, kf);
;     asm volatile("s_waitcnt vmcnt(0) lgkmcnt(0)" ::: "memory");
;     WBAR();
;     exp_pack(S0, l0, P0[0], P0[1]); exp_pack(S1, l1, P1[0], P1[1]);
;     WBAR();
.LBB0_102:
	s_and_b32 s3, s53, 0x2000
	s_xor_b32 s13, s3, 0x2000
	s_add_i32 s15, s13, s49
	s_add_i32 s13, s13, s48
	s_mov_b32 s52, m0
	s_mov_b32 m0, s13
	s_nop 0
	global_load_lds_dwordx4 v168, s[10:11]
	s_mov_b32 m0, s52
	v_add_u32_e32 v82, s3, v170
	s_mov_b32 s13, m0
	s_mov_b32 m0, s15
	s_nop 0
	global_load_lds_dwordx4 v169, s[34:35]
	s_mov_b32 m0, s13
	v_add_u32_e32 v178, v82, v171
	ds_read_b128 v[146:149], v178
	s_waitcnt lgkmcnt(4)
	v_mfma_f32_32x32x16_bf16 v[50:65], v[142:145], v[74:77], v[50:65]
	v_add_u32_e32 v179, v82, v172
	ds_read_b128 v[150:153], v179
	v_add_u32_e32 v175, v82, v173
	v_add_u32_e32 v176, v82, v174
	ds_read_b128 v[154:157], v175
	ds_read_b128 v[158:161], v176
	v_mfma_f32_32x32x16_bf16 v[18:33], v[142:145], v[78:81], v[18:33]
	s_waitcnt lgkmcnt(6)
	v_mfma_f32_32x32x16_bf16 v[34:49], v[138:141], v[74:77], v[34:49]
	v_mfma_f32_32x32x16_bf16 v[2:17], v[138:141], v[78:81], v[2:17]
	s_waitcnt lgkmcnt(5)
	v_mfma_f32_32x32x16_bf16 v[50:65], v[134:137], v[70:73], v[50:65]
	v_mfma_f32_32x32x16_bf16 v[18:33], v[134:137], v[66:69], v[18:33]
	s_waitcnt lgkmcnt(4)
	v_mfma_f32_32x32x16_bf16 v[34:49], v[130:133], v[70:73], v[34:49]
	v_mfma_f32_32x32x16_bf16 v[2:17], v[130:133], v[66:69], v[2:17]
	ds_read_b128 v[142:145], v178 offset:16384
	ds_read_b128 v[134:137], v179 offset:16384
	ds_read_b128 v[138:141], v178 offset:20480
	ds_read_b128 v[130:133], v179 offset:20480
	s_waitcnt lgkmcnt(7)
	v_mfma_f32_32x32x16_bf16 v[66:81], v[146:149], v[126:129], 0
	v_mfma_f32_32x32x16_bf16 v[82:97], v[146:149], v[118:121], 0
	s_waitcnt lgkmcnt(6)
	v_mfma_f32_32x32x16_bf16 v[66:81], v[150:153], v[122:125], v[66:81]
	v_mfma_f32_32x32x16_bf16 v[82:97], v[150:153], v[114:117], v[82:97]
	s_waitcnt lgkmcnt(5)
	v_mfma_f32_32x32x16_bf16 v[66:81], v[154:157], v[110:113], v[66:81]
	v_mfma_f32_32x32x16_bf16 v[82:97], v[154:157], v[106:109], v[82:97]
	s_waitcnt lgkmcnt(4)
	v_mfma_f32_32x32x16_bf16 v[66:81], v[158:161], v[98:101], v[66:81]
	v_mfma_f32_32x32x16_bf16 v[82:97], v[158:161], v[102:105], v[82:97]
	ds_read_b128 v[146:149], v178 offset:4096
	ds_read_b128 v[150:153], v179 offset:4096
	ds_read_b128 v[154:157], v175 offset:4096
	ds_read_b128 v[158:161], v176 offset:4096
	s_barrier
	s_nop 6
	v_exp_f32_e32 v82, v82
	v_exp_f32_e32 v178, v83
	v_exp_f32_e32 v84, v84
	v_exp_f32_e32 v180, v85
	v_exp_f32_e32 v83, v66
	v_exp_f32_e32 v179, v67
	v_exp_f32_e32 v85, v68
	v_exp_f32_e32 v181, v69
	v_exp_f32_e32 v86, v86
	v_exp_f32_e32 v182, v87
	v_exp_f32_e32 v88, v88
	v_exp_f32_e32 v184, v89
	v_exp_f32_e32 v87, v70
	v_exp_f32_e32 v183, v71
	v_exp_f32_e32 v89, v72
	v_exp_f32_e32 v185, v73
	v_exp_f32_e32 v90, v90
	v_exp_f32_e32 v186, v91
	v_exp_f32_e32 v92, v92
	v_exp_f32_e32 v188, v93
	v_exp_f32_e32 v91, v74
	v_exp_f32_e32 v187, v75
	v_exp_f32_e32 v93, v76
	v_exp_f32_e32 v189, v77
	v_exp_f32_e32 v94, v94
	v_exp_f32_e32 v206, v95
	v_exp_f32_e32 v96, v96
	v_exp_f32_e32 v208, v97
	v_exp_f32_e32 v95, v78
	v_exp_f32_e32 v207, v79
	v_exp_f32_e32 v97, v80
	v_exp_f32_e32 v209, v81
	v_add_f32_e32 v74, v82, v178
	v_add_f32_e32 v75, v83, v179
	v_add_f32_e32 v76, v84, v180
	v_add_f32_e32 v77, v85, v181
	v_add_f32_e32 v78, v88, v184
	v_add_f32_e32 v79, v89, v185
	v_add_f32_e32 v74, v74, v76
	v_add_f32_e32 v75, v75, v77
	v_add_f32_e32 v76, v86, v182
	v_add_f32_e32 v77, v87, v183
	v_add_f32_e32 v80, v92, v188
	v_add_f32_e32 v81, v93, v189
	v_add_f32_e32 v76, v76, v78
	v_add_f32_e32 v77, v77, v79
	v_add_f32_e32 v78, v90, v186
	v_add_f32_e32 v79, v91, v187
	v_add_f32_e32 v210, v96, v208
	v_add_f32_e32 v211, v97, v209
	v_add_f32_e32 v78, v78, v80
	v_add_f32_e32 v79, v79, v81
	v_add_f32_e32 v80, v94, v206
	v_add_f32_e32 v81, v95, v207
	v_add_f32_e32 v74, v74, v76
	v_add_f32_e32 v75, v75, v77
	v_add_f32_e32 v80, v80, v210
	v_add_f32_e32 v81, v81, v211
	v_cvt_pk_bf16_f32 v66, v82, v178
	v_cvt_pk_bf16_f32 v67, v84, v180
	v_cvt_pk_bf16_f32 v68, v86, v182
	v_cvt_pk_bf16_f32 v69, v88, v184
	v_cvt_pk_bf16_f32 v70, v90, v186
	s_nop 0
	v_add_f32_e32 v76, v78, v80
	v_add_f32_e32 v77, v79, v81
	v_cvt_pk_bf16_f32 v71, v92, v188
	v_cvt_pk_bf16_f32 v72, v94, v206
	v_cvt_pk_bf16_f32 v73, v96, v208
	v_cvt_pk_bf16_f32 v78, v91, v187
	v_cvt_pk_bf16_f32 v79, v93, v189
	s_nop 0
	v_add_f32_e32 v210, v74, v76
	v_add_f32_e32 v211, v75, v77
	v_cvt_pk_bf16_f32 v74, v83, v179
	v_cvt_pk_bf16_f32 v75, v85, v181
	v_cvt_pk_bf16_f32 v76, v87, v183
	v_cvt_pk_bf16_f32 v77, v89, v185
	v_cvt_pk_bf16_f32 v80, v95, v207
	v_cvt_pk_bf16_f32 v81, v97, v209
	s_barrier
	s_waitcnt lgkmcnt(7)
	v_mfma_f32_32x32x16_bf16 v[50:65], v[142:145], v[66:69], v[50:65]
	v_mfma_f32_32x32x16_bf16 v[18:33], v[142:145], v[74:77], v[18:33]
	s_waitcnt lgkmcnt(5)
	v_mfma_f32_32x32x16_bf16 v[34:49], v[138:141], v[66:69], v[34:49]
	v_mfma_f32_32x32x16_bf16 v[2:17], v[138:141], v[74:77], v[2:17]
	v_mfma_f32_32x32x16_bf16 v[50:65], v[134:137], v[70:73], v[50:65]
	v_mfma_f32_32x32x16_bf16 v[18:33], v[134:137], v[78:81], v[18:33]
	s_waitcnt lgkmcnt(4)
	v_mfma_f32_32x32x16_bf16 v[34:49], v[130:133], v[70:73], v[34:49]
	v_mfma_f32_32x32x16_bf16 v[2:17], v[130:133], v[78:81], v[2:17]
	ds_read_b128 v[142:145], v175 offset:16384
	ds_read_b128 v[138:141], v175 offset:20480
	ds_read_b128 v[134:137], v176 offset:16384
	ds_read_b128 v[130:133], v176 offset:20480
	s_waitcnt vmcnt(0) lgkmcnt(0)
	s_waitcnt lgkmcnt(7)
	v_mfma_f32_32x32x16_bf16 v[66:81], v[146:149], v[126:129], 0
	v_mfma_f32_32x32x16_bf16 v[82:97], v[146:149], v[118:121], 0
	v_add_f32_e64 v146, v162, v210
	v_add_f32_e64 v147, v163, v211
	s_waitcnt lgkmcnt(6)
	v_mfma_f32_32x32x16_bf16 v[66:81], v[150:153], v[122:125], v[66:81]
	v_mfma_f32_32x32x16_bf16 v[82:97], v[150:153], v[114:117], v[82:97]
	s_waitcnt lgkmcnt(5)
	v_mfma_f32_32x32x16_bf16 v[66:81], v[154:157], v[110:113], v[66:81]
	v_mfma_f32_32x32x16_bf16 v[82:97], v[154:157], v[106:109], v[82:97]
	s_waitcnt lgkmcnt(4)
	v_mfma_f32_32x32x16_bf16 v[66:81], v[158:161], v[98:101], v[66:81]
	v_mfma_f32_32x32x16_bf16 v[82:97], v[158:161], v[102:105], v[82:97]
	s_barrier
; #define ATT_QK(S0_, S1_, kf_) do { \
;     _Pragma("unroll") for (int i_ = 0; i_ < 16; ++i_) { S0_[i_] = 0.f; S1_[i_] = 0.f; } \
;     _Pragma("unroll") for (int kk_ = 0; kk_ < 4; ++kk_) { \
;       S0_ = __builtin_amdgcn_mfma_f32_32x32x16_bf16(kf_[kk_], qf[0][kk_], S0_, 0, 0, 0); \
;       S1_ = __builtin_amdgcn_mfma_f32_32x32x16_bf16(kf_[kk_], qf[1][kk_], S1_, 0, 0, 0); } } while (0)
; #define ATT_PV(vf_, P0_, P1_) do { \
;     _Pragma("unroll") for (int c_ = 0; c_ < 2; ++c_) \
;     _Pragma("unroll") for (int db_ = 0; db_ < 2; ++db_) { \
;       O[db_][0] = __builtin_amdgcn_mfma_f32_32x32x16_bf16(vf_[db_ * 2 + c_], P0_[c_], O[db_][0], 0, 0, 0); \
;       O[db_][1] = __builtin_amdgcn_mfma_f32_32x32x16_bf16(vf_[db_ * 2 + c_], P1_[c_], O[db_][1], 0, 0, 0); } } while (0)
; #define WBAR() do { __builtin_amdgcn_sched_barrier(0); __builtin_amdgcn_s_barrier(); __builtin_amdgcn_sched_barrier(0); } while (0)
; __device__ __forceinline__ void exp_pack(f32x16& s, float& l, bf16x8& p0, bf16x8& p1) {
; #pragma unroll
;   for (int i = 0; i < 16; ++i) s[i] = __builtin_amdgcn_exp2f(s[i]);
;   const float a0 = (s[0] + s[1]) + (s[2] + s[3]), a1 = (s[4] + s[5]) + (s[6] + s[7]);
;   const float a2 = (s[8] + s[9]) + (s[10] + s[11]), a3 = (s[12] + s[13]) + (s[14] + s[15]);
;   l += (a0 + a1) + (a2 + a3);
;   p0 = pack8(s, 0); p1 = pack8(s, 8);
; }
; __device__ __forceinline__ void attn_item_fast(const u16* __restrict__ Qg, const u16* __restrict__ Kg, const u16* __restrict__ Vtg,
;                                                u16* __restrict__ Og, const int L, char* smem, const int tid) {
;     ...
;     exp_pack(S0, l0, P0[0], P0[1]); exp_pack(S1, l1, P1[0], P1[1]);
;     WBAR();
;     ATT_PV(vf, P0, P1);
;     ld_vf<1>(vf, Vb, r32, hi, sw);
;     ATT_QK(S0, S1, kf);
;     asm volatile("s_waitcnt vmcnt(0) lgkmcnt(0)" ::: "memory");
;     WBAR();
;     exp_pack(S0, l0, P0[0], P0[1]); exp_pack(S1, l1, P1[0], P1[1]);
;     WBAR();
	s_nop 10
	v_exp_f32_e32 v82, v82
	v_exp_f32_e32 v148, v83
	v_exp_f32_e32 v84, v84
	v_exp_f32_e32 v150, v85
	v_exp_f32_e32 v83, v66
	v_exp_f32_e32 v149, v67
	v_exp_f32_e32 v85, v68
	v_exp_f32_e32 v151, v69
	v_exp_f32_e32 v86, v86
	v_exp_f32_e32 v152, v87
	v_exp_f32_e32 v88, v88
	v_exp_f32_e32 v154, v89
	v_exp_f32_e32 v87, v70
	v_exp_f32_e32 v153, v71
	v_exp_f32_e32 v89, v72
	v_exp_f32_e32 v155, v73
	v_exp_f32_e32 v90, v90
	v_exp_f32_e32 v156, v91
	v_exp_f32_e32 v92, v92
	v_exp_f32_e32 v158, v93
	v_exp_f32_e32 v91, v74
	v_exp_f32_e32 v157, v75
	v_exp_f32_e32 v93, v76
	v_exp_f32_e32 v159, v77
	v_exp_f32_e32 v94, v94
	v_exp_f32_e32 v160, v95
	v_exp_f32_e32 v96, v96
	v_exp_f32_e32 v178, v97
	v_exp_f32_e32 v95, v78
	v_exp_f32_e32 v161, v79
	v_exp_f32_e32 v97, v80
	v_exp_f32_e32 v179, v81
	v_add_f32_e32 v66, v82, v148
	v_add_f32_e32 v67, v83, v149
	v_add_f32_e32 v68, v84, v150
	v_add_f32_e32 v69, v85, v151
	v_add_f32_e32 v70, v88, v154
	v_add_f32_e32 v71, v89, v155
	v_add_f32_e32 v66, v66, v68
	v_add_f32_e32 v67, v67, v69
	v_add_f32_e32 v68, v86, v152
	v_add_f32_e32 v69, v87, v153
	v_add_f32_e32 v72, v92, v158
	v_add_f32_e32 v73, v93, v159
	v_add_f32_e32 v68, v68, v70
	v_add_f32_e32 v69, v69, v71
	v_add_f32_e32 v70, v90, v156
	v_add_f32_e32 v71, v91, v157
	v_add_f32_e32 v74, v96, v178
	v_add_f32_e32 v75, v97, v179
	v_add_f32_e32 v70, v70, v72
	v_add_f32_e32 v71, v71, v73
	v_add_f32_e32 v72, v94, v160
	v_add_f32_e32 v73, v95, v161
	v_add_f32_e32 v66, v66, v68
	v_add_f32_e32 v67, v67, v69
	v_add_f32_e32 v72, v72, v74
	v_add_f32_e32 v73, v73, v75
	v_cvt_pk_bf16_f32 v74, v82, v148
	v_cvt_pk_bf16_f32 v75, v84, v150
	v_cvt_pk_bf16_f32 v76, v86, v152
	v_cvt_pk_bf16_f32 v77, v88, v154
	v_cvt_pk_bf16_f32 v78, v83, v149
	s_nop 0
	v_add_f32_e32 v68, v70, v72
	v_add_f32_e32 v69, v71, v73
	v_cvt_pk_bf16_f32 v70, v90, v156
	v_cvt_pk_bf16_f32 v71, v92, v158
	v_cvt_pk_bf16_f32 v72, v94, v160
	v_cvt_pk_bf16_f32 v73, v96, v178
	v_cvt_pk_bf16_f32 v79, v85, v151
	s_nop 0
	v_add_f32_e32 v66, v66, v68
	v_add_f32_e32 v67, v67, v69
	v_cvt_pk_bf16_f32 v80, v87, v153
	v_cvt_pk_bf16_f32 v81, v89, v155
	v_cvt_pk_bf16_f32 v68, v95, v161
	v_cvt_pk_bf16_f32 v69, v97, v179
	s_nop 0
	v_add_f32_e32 v162, v146, v66
	v_add_f32_e32 v163, v147, v67
	v_cvt_pk_bf16_f32 v66, v91, v157
	v_cvt_pk_bf16_f32 v67, v93, v159
	s_barrier
	s_addk_i32 s53, 0x2000
	s_add_u32 s10, s10, 0x8000
	s_addc_u32 s11, s11, 0
	s_add_u32 s34, s34, 0x80
	s_addc_u32 s35, s35, 0
	s_cmp_eq_u32 s53, 0x3e000
	s_cbranch_scc0 .LBB0_102
	v_add_u32_e32 v175, v170, v171
	ds_read_b128 v[146:149], v175 offset:8192
	s_waitcnt lgkmcnt(4)
	v_mfma_f32_32x32x16_bf16 v[50:65], v[142:145], v[74:77], v[50:65]
	v_add_u32_e32 v176, v170, v172
	ds_read_b128 v[150:153], v176 offset:8192
	v_add_u32_e32 v205, v170, v173
	ds_read_b128 v[154:157], v205 offset:8192
	v_add_u32_e32 v226, v170, v174
	ds_read_b128 v[158:161], v226 offset:8192
	ds_read_b128 v[178:181], v175 offset:24576
	ds_read_b128 v[182:185], v176 offset:24576
	ds_read_b128 v[186:189], v175 offset:28672
	ds_read_b128 v[206:209], v176 offset:28672
	v_mfma_f32_32x32x16_bf16 v[18:33], v[142:145], v[78:81], v[18:33]
	ds_read_b128 v[210:213], v175 offset:12288
	ds_read_b128 v[214:217], v176 offset:12288
	ds_read_b128 v[218:221], v205 offset:12288
	ds_read_b128 v[222:225], v226 offset:12288
	s_waitcnt lgkmcnt(14)
	v_mfma_f32_32x32x16_bf16 v[34:49], v[138:141], v[74:77], v[34:49]
	v_mfma_f32_32x32x16_bf16 v[2:17], v[138:141], v[78:81], v[2:17]
	s_waitcnt lgkmcnt(13)
	v_mfma_f32_32x32x16_bf16 v[50:65], v[134:137], v[70:73], v[50:65]
	v_mfma_f32_32x32x16_bf16 v[18:33], v[134:137], v[66:69], v[18:33]
	s_waitcnt lgkmcnt(12)
	v_mfma_f32_32x32x16_bf16 v[34:49], v[130:133], v[70:73], v[34:49]
	v_mfma_f32_32x32x16_bf16 v[2:17], v[130:133], v[66:69], v[2:17]
	s_waitcnt lgkmcnt(11)
	v_mfma_f32_32x32x16_bf16 v[82:97], v[146:149], v[118:121], 0
	v_mfma_f32_32x32x16_bf16 v[66:81], v[146:149], v[126:129], 0
	s_waitcnt lgkmcnt(10)
	v_mfma_f32_32x32x16_bf16 v[82:97], v[150:153], v[114:117], v[82:97]
	v_mfma_f32_32x32x16_bf16 v[66:81], v[150:153], v[122:125], v[66:81]
	s_waitcnt lgkmcnt(9)
	v_mfma_f32_32x32x16_bf16 v[82:97], v[154:157], v[106:109], v[82:97]
	v_mfma_f32_32x32x16_bf16 v[66:81], v[154:157], v[110:113], v[66:81]
	s_waitcnt lgkmcnt(8)
	v_mfma_f32_32x32x16_bf16 v[82:97], v[158:161], v[102:105], v[82:97]
	v_mfma_f32_32x32x16_bf16 v[66:81], v[158:161], v[98:101], v[66:81]
	s_barrier
; #define ATT_QK(S0_, S1_, kf_) do { \
;     _Pragma("unroll") for (int i_ = 0; i_ < 16; ++i_) { S0_[i_] = 0.f; S1_[i_] = 0.f; } \
;     _Pragma("unroll") for (int kk_ = 0; kk_ < 4; ++kk_) { \
;       S0_ = __builtin_amdgcn_mfma_f32_32x32x16_bf16(kf_[kk_], qf[0][kk_], S0_, 0, 0, 0); \
;       S1_ = __builtin_amdgcn_mfma_f32_32x32x16_bf16(kf_[kk_], qf[1][kk_], S1_, 0, 0, 0); } } while (0)
; #define ATT_PV(vf_, P0_, P1_) do { \
;     _Pragma("unroll") for (int c_ = 0; c_ < 2; ++c_) \
;     _Pragma("unroll") for (int db_ = 0; db_ < 2; ++db_) { \
;       O[db_][0] = __builtin_amdgcn_mfma_f32_32x32x16_bf16(vf_[db_ * 2 + c_], P0_[c_], O[db_][0], 0, 0, 0); \
;       O[db_][1] = __builtin_amdgcn_mfma_f32_32x32x16_bf16(vf_[db_ * 2 + c_], P1_[c_], O[db_][1], 0, 0, 0); } } while (0)
; #define WBAR() do { __builtin_amdgcn_sched_barrier(0); __builtin_amdgcn_s_barrier(); __builtin_amdgcn_sched_barrier(0); } while (0)
; __device__ __forceinline__ void attn_item_fast(const u16* __restrict__ Qg, const u16* __restrict__ Kg, const u16* __restrict__ Vtg,
;                                                u16* __restrict__ Og, const int L, char* smem, const int tid) {
;     ...
;     ld_kf<0>(kf, Kb, r32, hi, sw);
;     ATT_PV(vf, P0, P1);
;     ld_vf<0>(vf, Vb, r32, hi, sw);
;     ATT_QK(S0, S1, kf);
;     ld_kf<1>(kf, Kb, r32, hi, sw);
;     WBAR();
;     exp_pack(S0, l0, P0[0], P0[1]); exp_pack(S1, l1, P1[0], P1[1]);
;     WBAR();
;     ATT_PV(vf, P0, P1);
;     ld_vf<1>(vf, Vb, r32, hi, sw);
;     ATT_QK(S0, S1, kf);
;     asm volatile("s_waitcnt vmcnt(0) lgkmcnt(0)" ::: "memory");
;     WBAR();
;     exp_pack(S0, l0, P0[0], P0[1]); exp_pack(S1, l1, P1[0], P1[1]);
;     WBAR();
;   }
;   if (half == 0) WBAR();
	s_nop 9
	v_exp_f32_e32 v138, v82
	v_exp_f32_e32 v144, v83
	v_exp_f32_e32 v132, v84
	v_exp_f32_e32 v139, v85
	v_exp_f32_e32 v133, v86
	v_exp_f32_e32 v140, v87
	v_exp_f32_e32 v141, v88
	v_exp_f32_e32 v145, v89
	v_exp_f32_e32 v134, v90
	v_exp_f32_e32 v142, v91
	v_exp_f32_e32 v130, v92
	v_exp_f32_e32 v135, v93
	v_exp_f32_e32 v131, v94
	v_exp_f32_e32 v136, v95
	v_exp_f32_e32 v137, v96
	v_exp_f32_e32 v143, v97
	v_exp_f32_e32 v146, v66
	v_exp_f32_e32 v147, v67
	v_exp_f32_e32 v148, v68
	v_exp_f32_e32 v151, v69
	v_exp_f32_e32 v149, v70
	v_exp_f32_e32 v152, v71
	v_exp_f32_e32 v153, v72
	v_exp_f32_e32 v157, v73
	v_exp_f32_e32 v150, v74
	v_exp_f32_e32 v154, v75
	v_exp_f32_e32 v155, v76
	v_exp_f32_e32 v158, v77
	v_exp_f32_e32 v156, v78
	v_exp_f32_e32 v159, v79
	v_exp_f32_e32 v160, v80
	v_exp_f32_e32 v161, v81
	v_cvt_pk_bf16_f32 v82, v138, v144
	v_cvt_pk_bf16_f32 v83, v132, v139
	v_cvt_pk_bf16_f32 v84, v133, v140
	v_cvt_pk_bf16_f32 v85, v141, v145
	v_cvt_pk_bf16_f32 v86, v134, v142
	v_cvt_pk_bf16_f32 v87, v130, v135
	v_cvt_pk_bf16_f32 v88, v131, v136
	v_cvt_pk_bf16_f32 v89, v137, v143
	v_cvt_pk_bf16_f32 v66, v146, v147
	v_cvt_pk_bf16_f32 v67, v148, v151
	v_cvt_pk_bf16_f32 v68, v149, v152
	v_cvt_pk_bf16_f32 v69, v153, v157
	v_cvt_pk_bf16_f32 v70, v150, v154
	v_cvt_pk_bf16_f32 v71, v155, v158
	v_cvt_pk_bf16_f32 v72, v156, v159
	v_cvt_pk_bf16_f32 v73, v160, v161
	s_barrier
	s_waitcnt lgkmcnt(7)
	v_mfma_f32_32x32x16_bf16 v[50:65], v[178:181], v[82:85], v[50:65]
	v_mfma_f32_32x32x16_bf16 v[18:33], v[178:181], v[66:69], v[18:33]
	s_waitcnt lgkmcnt(5)
	v_mfma_f32_32x32x16_bf16 v[34:49], v[186:189], v[82:85], v[34:49]
	v_mfma_f32_32x32x16_bf16 v[2:17], v[186:189], v[66:69], v[2:17]
	v_mfma_f32_32x32x16_bf16 v[50:65], v[182:185], v[86:89], v[50:65]
	v_mfma_f32_32x32x16_bf16 v[18:33], v[182:185], v[70:73], v[18:33]
	s_waitcnt lgkmcnt(4)
	v_mfma_f32_32x32x16_bf16 v[34:49], v[206:209], v[86:89], v[34:49]
	v_mfma_f32_32x32x16_bf16 v[2:17], v[206:209], v[70:73], v[2:17]
	s_waitcnt lgkmcnt(3)
	v_mfma_f32_32x32x16_bf16 v[82:97], v[210:213], v[118:121], 0
	v_mfma_f32_32x32x16_bf16 v[66:81], v[210:213], v[126:129], 0
	s_waitcnt lgkmcnt(2)
	v_mfma_f32_32x32x16_bf16 v[82:97], v[214:217], v[114:117], v[82:97]
	v_mfma_f32_32x32x16_bf16 v[66:81], v[214:217], v[122:125], v[66:81]
	s_waitcnt lgkmcnt(1)
	v_mfma_f32_32x32x16_bf16 v[82:97], v[218:221], v[106:109], v[82:97]
	v_mfma_f32_32x32x16_bf16 v[66:81], v[218:221], v[110:113], v[66:81]
	s_waitcnt lgkmcnt(0)
	v_mfma_f32_32x32x16_bf16 v[82:97], v[222:225], v[102:105], v[82:97]
	ds_read_b128 v[114:117], v205 offset:24576
	ds_read_b128 v[110:113], v205 offset:28672
	ds_read_b128 v[106:109], v226 offset:24576
	ds_read_b128 v[102:105], v226 offset:28672
	s_waitcnt vmcnt(0) lgkmcnt(0)
	v_mfma_f32_32x32x16_bf16 v[66:81], v[222:225], v[98:101], v[66:81]
	s_barrier
	s_nop 5
	v_exp_f32_e32 v98, v82
	v_exp_f32_e32 v99, v83
	v_exp_f32_e32 v100, v84
	v_exp_f32_e32 v119, v85
	v_exp_f32_e32 v101, v86
	v_exp_f32_e32 v120, v87
	v_exp_f32_e32 v121, v88
	v_exp_f32_e32 v122, v89
	v_exp_f32_e32 v90, v90
	v_exp_f32_e32 v91, v91
	v_exp_f32_e32 v92, v92
	v_exp_f32_e32 v118, v93
	v_exp_f32_e32 v93, v94
	v_exp_f32_e32 v94, v95
	v_exp_f32_e32 v95, v96
	v_exp_f32_e32 v96, v97
	v_exp_f32_e32 v175, v66
	v_exp_f32_e32 v176, v67
	v_exp_f32_e32 v178, v68
	v_exp_f32_e32 v179, v69
	v_exp_f32_e32 v97, v70
	v_exp_f32_e32 v124, v71
	v_exp_f32_e32 v125, v72
	v_exp_f32_e32 v128, v73
	v_exp_f32_e32 v123, v74
	v_exp_f32_e32 v126, v75
	v_exp_f32_e32 v127, v76
	v_exp_f32_e32 v129, v77
	v_exp_f32_e32 v74, v78
	v_exp_f32_e32 v75, v79
	v_exp_f32_e32 v76, v80
	v_exp_f32_e32 v77, v81
	v_cvt_pk_bf16_f32 v86, v98, v99
	v_cvt_pk_bf16_f32 v87, v100, v119
	v_cvt_pk_bf16_f32 v88, v101, v120
	v_cvt_pk_bf16_f32 v89, v121, v122
	v_cvt_pk_bf16_f32 v82, v90, v91
	v_cvt_pk_bf16_f32 v83, v92, v118
	v_cvt_pk_bf16_f32 v84, v93, v94
	v_cvt_pk_bf16_f32 v85, v95, v96
	v_cvt_pk_bf16_f32 v70, v175, v176
	v_cvt_pk_bf16_f32 v71, v178, v179
	v_cvt_pk_bf16_f32 v72, v97, v124
	v_cvt_pk_bf16_f32 v73, v125, v128
	v_cvt_pk_bf16_f32 v66, v123, v126
	v_cvt_pk_bf16_f32 v67, v127, v129
	v_cvt_pk_bf16_f32 v68, v74, v75
	v_cvt_pk_bf16_f32 v69, v76, v77
	s_barrier
	s_cmpk_lt_u32 s14, 0x100
	s_cbranch_scc0 .LBB0_98
	s_barrier
	s_branch .LBB0_98
